# variant: in-proj tiles dynamic with one-tile lead (ticket after K-loop, read after an extra latch barrier), no next-tile prefetch
# baseline (speedup 1.0000x reference)
; DI void phase_inproj(const Params& p, int layer, char* lds) {
;     ...
;   for (int u = bl; u < per_x; u += nbl) {
;     const int lr = u / NTN, nt = u % NTN;
;     const int mt = xcd_ok ? lr * 8 + xj : lr, m0 = mt * 256, n0 = nt * 256;
.LBB0_81:
	s_or_b64 exec, exec, s[4:5]
	s_barrier
	v_mov_b32_e32 v0, 0x23ff0
	ds_read_b32 v0, v0
	s_waitcnt lgkmcnt(0)
	s_nop 0
	v_readfirstlane_b32 s23, v0
	s_nop 3
	v_readlane_b32 s4, v254, 32
	s_cmp_lt_i32 s23, s4
	s_cbranch_scc0 .LBB0_152

; DI void phase_inproj(const Params& p, int layer, char* lds) {
;     ...
;   const bool xcd_ok = (gridDim.x % 8) == 0;
;   const int xj = xcd_ok ? (int)(blockIdx.x & 7) : 0, nbl = xcd_ok ? (int)(gridDim.x >> 3) : (int)gridDim.x;
;   const int bl = xcd_ok ? (int)(blockIdx.x >> 3) : (int)blockIdx.x, per_x = xcd_ok ? NTILES / 8 : NTILES;
;   for (int u = bl; u < per_x; u += nbl) {
;     const int lr = u / NTN, nt = u % NTN;
;     const int mt = xcd_ok ? lr * 8 + xj : lr, m0 = mt * 256, n0 = nt * 256;
.LBB0_88:
	s_or_b64 exec, exec, s[8:9]
	s_mov_b32 s32, 0
	v_readfirstlane_b32 s7, v184
	s_nop 3
	s_cmp_lg_u32 s7, 0
	s_cbranch_scc1 .Lipf_none
	v_readlane_b32 s10, v255, 36
	v_readlane_b32 s11, v255, 37
	s_lshl_b32 s12, s80, 5
	s_lshl_b32 s13, s28, 2
	s_add_i32 s12, s12, s13
	s_addk_i32 s12, 0x80
	s_add_u32 s10, s10, s12
	s_addc_u32 s11, s11, 0
	v_mov_b32_e32 v181, 1
	s_mov_b64 s[12:13], exec
	s_mov_b64 exec, 1
	global_atomic_add v180, v5, v181, s[10:11] sc0
	s_mov_b64 exec, s[12:13]

; DI void phase_inproj(const Params& p, int layer, char* lds) {
;     ...
;   for (int u = bl; u < per_x; u += nbl) {
;     const int lr = u / NTN, nt = u % NTN;
;     const int mt = xcd_ok ? lr * 8 + xj : lr, m0 = mt * 256, n0 = nt * 256;
.Lipe1_done:
	v_readfirstlane_b32 s5, v184
	s_nop 3
	s_cmp_lg_u32 s5, 0
	s_cbranch_scc1 .Ldt_nowr
	s_waitcnt vmcnt(8)
	s_mov_b64 s[8:9], exec
	s_mov_b64 exec, 1
	v_mov_b32_e32 v182, 0x23ff0
	v_add_u32_e32 v180, 32, v180
	ds_write_b32 v182, v180
	s_waitcnt lgkmcnt(0)
	s_mov_b64 exec, s[8:9]
